# conv-branch mixer item rewritten: filter taps hoisted, the next segment's eight loads in flight during the current segment's math (two register sets), sequence-boundary rows by select instead of branc
# speedup vs baseline: 1.0129x; 1.0108x over previous
.LBB0_766:
	s_sub_i32 s0, s25, s24
	v_readlane_b32 s1, v248, 23
	s_cmp_ge_i32 s25, s1
	s_mov_b64 s[22:23], -1
	s_cbranch_scc0 .LBB0_775
	s_ashr_i32 s1, s0, 31
	s_lshl_b64 s[12:13], s[0:1], 6
	s_add_u32 s38, s12, 0xffff8000
	s_addc_u32 s39, s13, -1
	s_waitcnt vmcnt(0)
	v_lshrrev_b32_e32 v100, 6, v178
	v_add_u32_e32 v100, s38, v100
	v_mov_b32_e32 v108, s78
	v_mov_b32_e32 v109, s79
	v_mad_u64_u32 v[94:95], s[12:13], v100, s77, v[108:109]
	v_and_b32_e32 v110, 63, v178
	v_lshlrev_b32_e32 v114, 5, v110
	v_lshlrev_b32_e32 v110, 4, v110
	v_add_u32_e32 v110, 0x1000, v110
	v_mov_b32_e32 v111, 0
	v_mov_b32_e32 v115, 0
	v_lshl_add_u64 v[94:95], v[94:95], 0, v[110:111]
	s_mov_b32 s16, 0xffffd680
	s_mov_b32 s17, -1
	s_movk_i32 s40, 0x2980
	s_mov_b32 s41, 0
	v_lshl_add_u64 v[96:97], v[94:95], 0, s[16:17]
	v_lshl_add_u64 v[98:99], v[94:95], 0, s[40:41]
	s_mov_b32 s14, 0xa600
	s_mov_b32 s15, 0
	v_readlane_b32 s12, v248, 6
	v_readlane_b32 s13, v248, 7
	s_nop 3
	v_lshl_add_u64 v[112:113], s[12:13], 0, v[114:115]
	s_movk_i32 s12, 0x1000
	s_mov_b32 s13, 0
	v_lshl_add_u64 v[116:117], v[112:113], 0, s[12:13]
	global_load_dwordx4 v[70:73], v[112:113], off
	global_load_dwordx4 v[74:77], v[112:113], off offset:16
	global_load_dwordx4 v[78:81], v[112:113], off offset:2048
	global_load_dwordx4 v[82:85], v[112:113], off offset:2064
	global_load_dwordx4 v[86:89], v[116:117], off
	global_load_dwordx4 v[90:93], v[116:117], off offset:16
	global_load_dwordx4 v[2:5], v[96:97], off offset:-704
	global_load_dwordx4 v[6:9], v[96:97], off offset:320
	global_load_dwordx4 v[10:13], v[94:95], off offset:-704
	global_load_dwordx4 v[14:17], v[94:95], off offset:320
	global_load_dwordx4 v[18:21], v[98:99], off offset:-704
	global_load_dwordx4 v[22:25], v[98:99], off offset:320
	global_load_dwordx4 v[26:29], v[94:95], off offset:-1728
	global_load_dwordx4 v[30:33], v[94:95], off offset:1344
	v_mov_b32_e32 v102, v94
	v_mov_b32_e32 v103, v95
	v_mov_b32_e32 v106, v100
	v_lshl_add_u64 v[94:95], v[94:95], 0, s[14:15]
	v_lshl_add_u64 v[96:97], v[96:97], 0, s[14:15]
	v_lshl_add_u64 v[98:99], v[98:99], 0, s[14:15]
	v_add_u32_e32 v100, 4, v100
	global_load_dword v144, v[112:113], off
	global_load_dwordx4 v[34:37], v[96:97], off offset:-704
	global_load_dwordx4 v[38:41], v[96:97], off offset:320
	global_load_dwordx4 v[42:45], v[94:95], off offset:-704
	global_load_dwordx4 v[46:49], v[94:95], off offset:320
	global_load_dwordx4 v[50:53], v[98:99], off offset:-704
	global_load_dwordx4 v[54:57], v[98:99], off offset:320
	global_load_dwordx4 v[58:61], v[94:95], off offset:-1728
	global_load_dwordx4 v[62:65], v[94:95], off offset:1344
	v_mov_b32_e32 v104, v94
	v_mov_b32_e32 v105, v95
	v_mov_b32_e32 v107, v100
	v_lshl_add_u64 v[94:95], v[94:95], 0, s[14:15]
	v_lshl_add_u64 v[96:97], v[96:97], 0, s[14:15]
	v_lshl_add_u64 v[98:99], v[98:99], 0, s[14:15]
	v_add_u32_e32 v100, 4, v100
	s_mov_b32 s1, 0
.Lcvb_loop:
	s_waitcnt vmcnt(9)
	v_and_b32_e32 v118, s46, v106
	v_cmp_lt_i32_e32 vcc, 0, v118
	v_cndmask_b32_e32 v2, 0, v2, vcc
	v_cndmask_b32_e32 v3, 0, v3, vcc
	v_cndmask_b32_e32 v4, 0, v4, vcc
	v_cndmask_b32_e32 v5, 0, v5, vcc
	v_cndmask_b32_e32 v6, 0, v6, vcc
	v_cndmask_b32_e32 v7, 0, v7, vcc
	v_cndmask_b32_e32 v8, 0, v8, vcc
	v_cndmask_b32_e32 v9, 0, v9, vcc
	v_cmp_gt_i32_e32 vcc, s50, v118
	v_cndmask_b32_e32 v18, 0, v18, vcc
	v_cndmask_b32_e32 v19, 0, v19, vcc
	v_cndmask_b32_e32 v20, 0, v20, vcc
	v_cndmask_b32_e32 v21, 0, v21, vcc
	v_cndmask_b32_e32 v22, 0, v22, vcc
	v_cndmask_b32_e32 v23, 0, v23, vcc
	v_cndmask_b32_e32 v24, 0, v24, vcc
	v_cndmask_b32_e32 v25, 0, v25, vcc
	v_lshlrev_b32_e32 v120, 16, v2
	v_and_b32_e32 v121, 0xffff0000, v2
	v_lshlrev_b32_e32 v122, 16, v6
	v_and_b32_e32 v123, 0xffff0000, v6
	v_pk_mul_f32 v[124:125], v[120:121], v[122:123]
	v_lshlrev_b32_e32 v120, 16, v10
	v_and_b32_e32 v121, 0xffff0000, v10
	v_lshlrev_b32_e32 v122, 16, v14
	v_and_b32_e32 v123, 0xffff0000, v14
	v_pk_mul_f32 v[126:127], v[120:121], v[122:123]
	v_lshlrev_b32_e32 v120, 16, v18
	v_and_b32_e32 v121, 0xffff0000, v18
	v_lshlrev_b32_e32 v122, 16, v22
	v_and_b32_e32 v123, 0xffff0000, v22
	v_pk_mul_f32 v[128:129], v[120:121], v[122:123]
	v_pk_mul_f32 v[134:135], v[124:125], v[70:71]
	v_pk_fma_f32 v[134:135], v[126:127], v[78:79], v[134:135]
	v_pk_fma_f32 v[134:135], v[128:129], v[86:87], v[134:135]
	v_lshlrev_b32_e32 v120, 16, v26
	v_and_b32_e32 v121, 0xffff0000, v26
	v_pk_mul_f32 v[134:135], v[120:121], v[134:135]
	v_lshlrev_b32_e32 v130, 16, v30
	v_and_b32_e32 v131, 0xffff0000, v30
	v_mul_f32_e32 v132, 0xbfb8aa3b, v130
	v_mul_f32_e32 v133, 0xbfb8aa3b, v131
	v_exp_f32_e32 v132, v132
	v_exp_f32_e32 v133, v133
	s_nop 0
	v_pk_add_f32 v[132:133], v[132:133], 1.0 op_sel_hi:[1,0]
	v_div_scale_f32 v136, s[12:13], v132, v132, v130
	v_rcp_f32_e32 v137, v136
	s_nop 0
	v_fma_f32 v138, -v136, v137, 1.0
	v_fmac_f32_e32 v137, v138, v137
	v_div_scale_f32 v138, vcc, v130, v132, v130
	v_mul_f32_e32 v139, v138, v137
	v_fma_f32 v119, -v136, v139, v138
	v_fmac_f32_e32 v139, v119, v137
	v_fma_f32 v136, -v136, v139, v138
	v_div_fmas_f32 v136, v136, v137, v139
	v_div_fixup_f32 v120, v136, v132, v130
	v_div_scale_f32 v136, s[12:13], v133, v133, v131
	v_rcp_f32_e32 v137, v136
	s_nop 0
	v_fma_f32 v138, -v136, v137, 1.0
	v_fmac_f32_e32 v137, v138, v137
	v_div_scale_f32 v138, vcc, v131, v133, v131
	v_mul_f32_e32 v139, v138, v137
	v_fma_f32 v119, -v136, v139, v138
	v_fmac_f32_e32 v139, v119, v137
	v_fma_f32 v136, -v136, v139, v138
	v_div_fmas_f32 v136, v136, v137, v139
	v_div_fixup_f32 v121, v136, v133, v131
	v_pk_mul_f32 v[134:135], v[134:135], v[120:121]
	v_cvt_pk_bf16_f32 v140, v134, v135
	v_lshlrev_b32_e32 v120, 16, v3
	v_and_b32_e32 v121, 0xffff0000, v3
	v_lshlrev_b32_e32 v122, 16, v7
	v_and_b32_e32 v123, 0xffff0000, v7
	v_pk_mul_f32 v[124:125], v[120:121], v[122:123]
	v_lshlrev_b32_e32 v120, 16, v11
	v_and_b32_e32 v121, 0xffff0000, v11
	v_lshlrev_b32_e32 v122, 16, v15
	v_and_b32_e32 v123, 0xffff0000, v15
	v_pk_mul_f32 v[126:127], v[120:121], v[122:123]
	v_lshlrev_b32_e32 v120, 16, v19
	v_and_b32_e32 v121, 0xffff0000, v19
	v_lshlrev_b32_e32 v122, 16, v23
	v_and_b32_e32 v123, 0xffff0000, v23
	v_pk_mul_f32 v[128:129], v[120:121], v[122:123]
	v_pk_mul_f32 v[134:135], v[124:125], v[72:73]
	v_pk_fma_f32 v[134:135], v[126:127], v[80:81], v[134:135]
	v_pk_fma_f32 v[134:135], v[128:129], v[88:89], v[134:135]
	v_lshlrev_b32_e32 v120, 16, v27
	v_and_b32_e32 v121, 0xffff0000, v27
	v_pk_mul_f32 v[134:135], v[120:121], v[134:135]
	v_lshlrev_b32_e32 v130, 16, v31
	v_and_b32_e32 v131, 0xffff0000, v31
	v_mul_f32_e32 v132, 0xbfb8aa3b, v130
	v_mul_f32_e32 v133, 0xbfb8aa3b, v131
	v_exp_f32_e32 v132, v132
	v_exp_f32_e32 v133, v133
	s_nop 0
	v_pk_add_f32 v[132:133], v[132:133], 1.0 op_sel_hi:[1,0]
	v_div_scale_f32 v136, s[12:13], v132, v132, v130
	v_rcp_f32_e32 v137, v136
	s_nop 0
	v_fma_f32 v138, -v136, v137, 1.0
	v_fmac_f32_e32 v137, v138, v137
	v_div_scale_f32 v138, vcc, v130, v132, v130
	v_mul_f32_e32 v139, v138, v137
	v_fma_f32 v119, -v136, v139, v138
	v_fmac_f32_e32 v139, v119, v137
	v_fma_f32 v136, -v136, v139, v138
	v_div_fmas_f32 v136, v136, v137, v139
	v_div_fixup_f32 v120, v136, v132, v130
	v_div_scale_f32 v136, s[12:13], v133, v133, v131
	v_rcp_f32_e32 v137, v136
	s_nop 0
	v_fma_f32 v138, -v136, v137, 1.0
	v_fmac_f32_e32 v137, v138, v137
	v_div_scale_f32 v138, vcc, v131, v133, v131
	v_mul_f32_e32 v139, v138, v137
	v_fma_f32 v119, -v136, v139, v138
	v_fmac_f32_e32 v139, v119, v137
	v_fma_f32 v136, -v136, v139, v138
	v_div_fmas_f32 v136, v136, v137, v139
	v_div_fixup_f32 v121, v136, v133, v131
	v_pk_mul_f32 v[134:135], v[134:135], v[120:121]
	v_cvt_pk_bf16_f32 v141, v134, v135
	v_lshlrev_b32_e32 v120, 16, v4
	v_and_b32_e32 v121, 0xffff0000, v4
	v_lshlrev_b32_e32 v122, 16, v8
	v_and_b32_e32 v123, 0xffff0000, v8
	v_pk_mul_f32 v[124:125], v[120:121], v[122:123]
	v_lshlrev_b32_e32 v120, 16, v12
	v_and_b32_e32 v121, 0xffff0000, v12
	v_lshlrev_b32_e32 v122, 16, v16
	v_and_b32_e32 v123, 0xffff0000, v16
	v_pk_mul_f32 v[126:127], v[120:121], v[122:123]
	v_lshlrev_b32_e32 v120, 16, v20
	v_and_b32_e32 v121, 0xffff0000, v20
	v_lshlrev_b32_e32 v122, 16, v24
	v_and_b32_e32 v123, 0xffff0000, v24
	v_pk_mul_f32 v[128:129], v[120:121], v[122:123]
	v_pk_mul_f32 v[134:135], v[124:125], v[74:75]
	v_pk_fma_f32 v[134:135], v[126:127], v[82:83], v[134:135]
	v_pk_fma_f32 v[134:135], v[128:129], v[90:91], v[134:135]
	v_lshlrev_b32_e32 v120, 16, v28
	v_and_b32_e32 v121, 0xffff0000, v28
	v_pk_mul_f32 v[134:135], v[120:121], v[134:135]
	v_lshlrev_b32_e32 v130, 16, v32
	v_and_b32_e32 v131, 0xffff0000, v32
	v_mul_f32_e32 v132, 0xbfb8aa3b, v130
	v_mul_f32_e32 v133, 0xbfb8aa3b, v131
	v_exp_f32_e32 v132, v132
	v_exp_f32_e32 v133, v133
	s_nop 0
	v_pk_add_f32 v[132:133], v[132:133], 1.0 op_sel_hi:[1,0]
	v_div_scale_f32 v136, s[12:13], v132, v132, v130
	v_rcp_f32_e32 v137, v136
	s_nop 0
	v_fma_f32 v138, -v136, v137, 1.0
	v_fmac_f32_e32 v137, v138, v137
	v_div_scale_f32 v138, vcc, v130, v132, v130
	v_mul_f32_e32 v139, v138, v137
	v_fma_f32 v119, -v136, v139, v138
	v_fmac_f32_e32 v139, v119, v137
	v_fma_f32 v136, -v136, v139, v138
	v_div_fmas_f32 v136, v136, v137, v139
	v_div_fixup_f32 v120, v136, v132, v130
	v_div_scale_f32 v136, s[12:13], v133, v133, v131
	v_rcp_f32_e32 v137, v136
	s_nop 0
	v_fma_f32 v138, -v136, v137, 1.0
	v_fmac_f32_e32 v137, v138, v137
	v_div_scale_f32 v138, vcc, v131, v133, v131
	v_mul_f32_e32 v139, v138, v137
	v_fma_f32 v119, -v136, v139, v138
	v_fmac_f32_e32 v139, v119, v137
	v_fma_f32 v136, -v136, v139, v138
	v_div_fmas_f32 v136, v136, v137, v139
	v_div_fixup_f32 v121, v136, v133, v131
	v_pk_mul_f32 v[134:135], v[134:135], v[120:121]
	v_cvt_pk_bf16_f32 v142, v134, v135
	v_lshlrev_b32_e32 v120, 16, v5
	v_and_b32_e32 v121, 0xffff0000, v5
	v_lshlrev_b32_e32 v122, 16, v9
	v_and_b32_e32 v123, 0xffff0000, v9
	v_pk_mul_f32 v[124:125], v[120:121], v[122:123]
	v_lshlrev_b32_e32 v120, 16, v13
	v_and_b32_e32 v121, 0xffff0000, v13
	v_lshlrev_b32_e32 v122, 16, v17
	v_and_b32_e32 v123, 0xffff0000, v17
	v_pk_mul_f32 v[126:127], v[120:121], v[122:123]
	v_lshlrev_b32_e32 v120, 16, v21
	v_and_b32_e32 v121, 0xffff0000, v21
	v_lshlrev_b32_e32 v122, 16, v25
	v_and_b32_e32 v123, 0xffff0000, v25
	v_pk_mul_f32 v[128:129], v[120:121], v[122:123]
	v_pk_mul_f32 v[134:135], v[124:125], v[76:77]
	v_pk_fma_f32 v[134:135], v[126:127], v[84:85], v[134:135]
	v_pk_fma_f32 v[134:135], v[128:129], v[92:93], v[134:135]
	v_lshlrev_b32_e32 v120, 16, v29
	v_and_b32_e32 v121, 0xffff0000, v29
	v_pk_mul_f32 v[134:135], v[120:121], v[134:135]
	v_lshlrev_b32_e32 v130, 16, v33
	v_and_b32_e32 v131, 0xffff0000, v33
	v_mul_f32_e32 v132, 0xbfb8aa3b, v130
	v_mul_f32_e32 v133, 0xbfb8aa3b, v131
	v_exp_f32_e32 v132, v132
	v_exp_f32_e32 v133, v133
	s_nop 0
	v_pk_add_f32 v[132:133], v[132:133], 1.0 op_sel_hi:[1,0]
	v_div_scale_f32 v136, s[12:13], v132, v132, v130
	v_rcp_f32_e32 v137, v136
	s_nop 0
	v_fma_f32 v138, -v136, v137, 1.0
	v_fmac_f32_e32 v137, v138, v137
	v_div_scale_f32 v138, vcc, v130, v132, v130
	v_mul_f32_e32 v139, v138, v137
	v_fma_f32 v119, -v136, v139, v138
	v_fmac_f32_e32 v139, v119, v137
	v_fma_f32 v136, -v136, v139, v138
	v_div_fmas_f32 v136, v136, v137, v139
	v_div_fixup_f32 v120, v136, v132, v130
	v_div_scale_f32 v136, s[12:13], v133, v133, v131
	v_rcp_f32_e32 v137, v136
	s_nop 0
	v_fma_f32 v138, -v136, v137, 1.0
	v_fmac_f32_e32 v137, v138, v137
	v_div_scale_f32 v138, vcc, v131, v133, v131
	v_mul_f32_e32 v139, v138, v137
	v_fma_f32 v119, -v136, v139, v138
	v_fmac_f32_e32 v139, v119, v137
	v_fma_f32 v136, -v136, v139, v138
	v_div_fmas_f32 v136, v136, v137, v139
	v_div_fixup_f32 v121, v136, v133, v131
	v_pk_mul_f32 v[134:135], v[134:135], v[120:121]
	v_cvt_pk_bf16_f32 v143, v134, v135
	global_store_dwordx4 v[102:103], v[140:143], off offset:1344
	global_load_dwordx4 v[2:5], v[96:97], off offset:-704
	global_load_dwordx4 v[6:9], v[96:97], off offset:320
	global_load_dwordx4 v[10:13], v[94:95], off offset:-704
	global_load_dwordx4 v[14:17], v[94:95], off offset:320
	global_load_dwordx4 v[18:21], v[98:99], off offset:-704
	global_load_dwordx4 v[22:25], v[98:99], off offset:320
	global_load_dwordx4 v[26:29], v[94:95], off offset:-1728
	global_load_dwordx4 v[30:33], v[94:95], off offset:1344
	v_mov_b32_e32 v102, v94
	v_mov_b32_e32 v103, v95
	v_mov_b32_e32 v106, v100
	v_lshl_add_u64 v[94:95], v[94:95], 0, s[14:15]
	v_lshl_add_u64 v[96:97], v[96:97], 0, s[14:15]
	v_lshl_add_u64 v[98:99], v[98:99], 0, s[14:15]
	v_add_u32_e32 v100, 4, v100
	s_waitcnt vmcnt(9)
	v_and_b32_e32 v118, s46, v107
	v_cmp_lt_i32_e32 vcc, 0, v118
	v_cndmask_b32_e32 v34, 0, v34, vcc
	v_cndmask_b32_e32 v35, 0, v35, vcc
	v_cndmask_b32_e32 v36, 0, v36, vcc
	v_cndmask_b32_e32 v37, 0, v37, vcc
	v_cndmask_b32_e32 v38, 0, v38, vcc
	v_cndmask_b32_e32 v39, 0, v39, vcc
	v_cndmask_b32_e32 v40, 0, v40, vcc
	v_cndmask_b32_e32 v41, 0, v41, vcc
	v_cmp_gt_i32_e32 vcc, s50, v118
	v_cndmask_b32_e32 v50, 0, v50, vcc
	v_cndmask_b32_e32 v51, 0, v51, vcc
	v_cndmask_b32_e32 v52, 0, v52, vcc
	v_cndmask_b32_e32 v53, 0, v53, vcc
	v_cndmask_b32_e32 v54, 0, v54, vcc
	v_cndmask_b32_e32 v55, 0, v55, vcc
	v_cndmask_b32_e32 v56, 0, v56, vcc
	v_cndmask_b32_e32 v57, 0, v57, vcc
	v_lshlrev_b32_e32 v120, 16, v34
	v_and_b32_e32 v121, 0xffff0000, v34
	v_lshlrev_b32_e32 v122, 16, v38
	v_and_b32_e32 v123, 0xffff0000, v38
	v_pk_mul_f32 v[124:125], v[120:121], v[122:123]
	v_lshlrev_b32_e32 v120, 16, v42
	v_and_b32_e32 v121, 0xffff0000, v42
	v_lshlrev_b32_e32 v122, 16, v46
	v_and_b32_e32 v123, 0xffff0000, v46
	v_pk_mul_f32 v[126:127], v[120:121], v[122:123]
	v_lshlrev_b32_e32 v120, 16, v50
	v_and_b32_e32 v121, 0xffff0000, v50
	v_lshlrev_b32_e32 v122, 16, v54
	v_and_b32_e32 v123, 0xffff0000, v54
	v_pk_mul_f32 v[128:129], v[120:121], v[122:123]
	v_pk_mul_f32 v[134:135], v[124:125], v[70:71]
	v_pk_fma_f32 v[134:135], v[126:127], v[78:79], v[134:135]
	v_pk_fma_f32 v[134:135], v[128:129], v[86:87], v[134:135]
	v_lshlrev_b32_e32 v120, 16, v58
	v_and_b32_e32 v121, 0xffff0000, v58
	v_pk_mul_f32 v[134:135], v[120:121], v[134:135]
	v_lshlrev_b32_e32 v130, 16, v62
	v_and_b32_e32 v131, 0xffff0000, v62
	v_mul_f32_e32 v132, 0xbfb8aa3b, v130
	v_mul_f32_e32 v133, 0xbfb8aa3b, v131
	v_exp_f32_e32 v132, v132
	v_exp_f32_e32 v133, v133
	s_nop 0
	v_pk_add_f32 v[132:133], v[132:133], 1.0 op_sel_hi:[1,0]
	v_div_scale_f32 v136, s[12:13], v132, v132, v130
	v_rcp_f32_e32 v137, v136
	s_nop 0
	v_fma_f32 v138, -v136, v137, 1.0
	v_fmac_f32_e32 v137, v138, v137
	v_div_scale_f32 v138, vcc, v130, v132, v130
	v_mul_f32_e32 v139, v138, v137
	v_fma_f32 v119, -v136, v139, v138
	v_fmac_f32_e32 v139, v119, v137
	v_fma_f32 v136, -v136, v139, v138
	v_div_fmas_f32 v136, v136, v137, v139
	v_div_fixup_f32 v120, v136, v132, v130
	v_div_scale_f32 v136, s[12:13], v133, v133, v131
	v_rcp_f32_e32 v137, v136
	s_nop 0
	v_fma_f32 v138, -v136, v137, 1.0
	v_fmac_f32_e32 v137, v138, v137
	v_div_scale_f32 v138, vcc, v131, v133, v131
	v_mul_f32_e32 v139, v138, v137
	v_fma_f32 v119, -v136, v139, v138
	v_fmac_f32_e32 v139, v119, v137
	v_fma_f32 v136, -v136, v139, v138
	v_div_fmas_f32 v136, v136, v137, v139
	v_div_fixup_f32 v121, v136, v133, v131
	v_pk_mul_f32 v[134:135], v[134:135], v[120:121]
	v_cvt_pk_bf16_f32 v140, v134, v135
	v_lshlrev_b32_e32 v120, 16, v35
	v_and_b32_e32 v121, 0xffff0000, v35
	v_lshlrev_b32_e32 v122, 16, v39
	v_and_b32_e32 v123, 0xffff0000, v39
	v_pk_mul_f32 v[124:125], v[120:121], v[122:123]
	v_lshlrev_b32_e32 v120, 16, v43
	v_and_b32_e32 v121, 0xffff0000, v43
	v_lshlrev_b32_e32 v122, 16, v47
	v_and_b32_e32 v123, 0xffff0000, v47
	v_pk_mul_f32 v[126:127], v[120:121], v[122:123]
	v_lshlrev_b32_e32 v120, 16, v51
	v_and_b32_e32 v121, 0xffff0000, v51
	v_lshlrev_b32_e32 v122, 16, v55
	v_and_b32_e32 v123, 0xffff0000, v55
	v_pk_mul_f32 v[128:129], v[120:121], v[122:123]
	v_pk_mul_f32 v[134:135], v[124:125], v[72:73]
	v_pk_fma_f32 v[134:135], v[126:127], v[80:81], v[134:135]
	v_pk_fma_f32 v[134:135], v[128:129], v[88:89], v[134:135]
	v_lshlrev_b32_e32 v120, 16, v59
	v_and_b32_e32 v121, 0xffff0000, v59
	v_pk_mul_f32 v[134:135], v[120:121], v[134:135]
	v_lshlrev_b32_e32 v130, 16, v63
	v_and_b32_e32 v131, 0xffff0000, v63
	v_mul_f32_e32 v132, 0xbfb8aa3b, v130
	v_mul_f32_e32 v133, 0xbfb8aa3b, v131
	v_exp_f32_e32 v132, v132
	v_exp_f32_e32 v133, v133
	s_nop 0
	v_pk_add_f32 v[132:133], v[132:133], 1.0 op_sel_hi:[1,0]
	v_div_scale_f32 v136, s[12:13], v132, v132, v130
	v_rcp_f32_e32 v137, v136
	s_nop 0
	v_fma_f32 v138, -v136, v137, 1.0
	v_fmac_f32_e32 v137, v138, v137
	v_div_scale_f32 v138, vcc, v130, v132, v130
	v_mul_f32_e32 v139, v138, v137
	v_fma_f32 v119, -v136, v139, v138
	v_fmac_f32_e32 v139, v119, v137
	v_fma_f32 v136, -v136, v139, v138
	v_div_fmas_f32 v136, v136, v137, v139
	v_div_fixup_f32 v120, v136, v132, v130
	v_div_scale_f32 v136, s[12:13], v133, v133, v131
	v_rcp_f32_e32 v137, v136
	s_nop 0
	v_fma_f32 v138, -v136, v137, 1.0
	v_fmac_f32_e32 v137, v138, v137
	v_div_scale_f32 v138, vcc, v131, v133, v131
	v_mul_f32_e32 v139, v138, v137
	v_fma_f32 v119, -v136, v139, v138
	v_fmac_f32_e32 v139, v119, v137
	v_fma_f32 v136, -v136, v139, v138
	v_div_fmas_f32 v136, v136, v137, v139
	v_div_fixup_f32 v121, v136, v133, v131
	v_pk_mul_f32 v[134:135], v[134:135], v[120:121]
	v_cvt_pk_bf16_f32 v141, v134, v135
	v_lshlrev_b32_e32 v120, 16, v36
	v_and_b32_e32 v121, 0xffff0000, v36
	v_lshlrev_b32_e32 v122, 16, v40
	v_and_b32_e32 v123, 0xffff0000, v40
	v_pk_mul_f32 v[124:125], v[120:121], v[122:123]
	v_lshlrev_b32_e32 v120, 16, v44
	v_and_b32_e32 v121, 0xffff0000, v44
	v_lshlrev_b32_e32 v122, 16, v48
	v_and_b32_e32 v123, 0xffff0000, v48
	v_pk_mul_f32 v[126:127], v[120:121], v[122:123]
	v_lshlrev_b32_e32 v120, 16, v52
	v_and_b32_e32 v121, 0xffff0000, v52
	v_lshlrev_b32_e32 v122, 16, v56
	v_and_b32_e32 v123, 0xffff0000, v56
	v_pk_mul_f32 v[128:129], v[120:121], v[122:123]
	v_pk_mul_f32 v[134:135], v[124:125], v[74:75]
	v_pk_fma_f32 v[134:135], v[126:127], v[82:83], v[134:135]
	v_pk_fma_f32 v[134:135], v[128:129], v[90:91], v[134:135]
	v_lshlrev_b32_e32 v120, 16, v60
	v_and_b32_e32 v121, 0xffff0000, v60
	v_pk_mul_f32 v[134:135], v[120:121], v[134:135]
	v_lshlrev_b32_e32 v130, 16, v64
	v_and_b32_e32 v131, 0xffff0000, v64
	v_mul_f32_e32 v132, 0xbfb8aa3b, v130
	v_mul_f32_e32 v133, 0xbfb8aa3b, v131
	v_exp_f32_e32 v132, v132
	v_exp_f32_e32 v133, v133
	s_nop 0
	v_pk_add_f32 v[132:133], v[132:133], 1.0 op_sel_hi:[1,0]
	v_div_scale_f32 v136, s[12:13], v132, v132, v130
	v_rcp_f32_e32 v137, v136
	s_nop 0
	v_fma_f32 v138, -v136, v137, 1.0
	v_fmac_f32_e32 v137, v138, v137
	v_div_scale_f32 v138, vcc, v130, v132, v130
	v_mul_f32_e32 v139, v138, v137
	v_fma_f32 v119, -v136, v139, v138
	v_fmac_f32_e32 v139, v119, v137
	v_fma_f32 v136, -v136, v139, v138
	v_div_fmas_f32 v136, v136, v137, v139
	v_div_fixup_f32 v120, v136, v132, v130
	v_div_scale_f32 v136, s[12:13], v133, v133, v131
	v_rcp_f32_e32 v137, v136
	s_nop 0
	v_fma_f32 v138, -v136, v137, 1.0
	v_fmac_f32_e32 v137, v138, v137
	v_div_scale_f32 v138, vcc, v131, v133, v131
	v_mul_f32_e32 v139, v138, v137
	v_fma_f32 v119, -v136, v139, v138
	v_fmac_f32_e32 v139, v119, v137
	v_fma_f32 v136, -v136, v139, v138
	v_div_fmas_f32 v136, v136, v137, v139
	v_div_fixup_f32 v121, v136, v133, v131
	v_pk_mul_f32 v[134:135], v[134:135], v[120:121]
	v_cvt_pk_bf16_f32 v142, v134, v135
	v_lshlrev_b32_e32 v120, 16, v37
	v_and_b32_e32 v121, 0xffff0000, v37
	v_lshlrev_b32_e32 v122, 16, v41
	v_and_b32_e32 v123, 0xffff0000, v41
	v_pk_mul_f32 v[124:125], v[120:121], v[122:123]
	v_lshlrev_b32_e32 v120, 16, v45
	v_and_b32_e32 v121, 0xffff0000, v45
	v_lshlrev_b32_e32 v122, 16, v49
	v_and_b32_e32 v123, 0xffff0000, v49
	v_pk_mul_f32 v[126:127], v[120:121], v[122:123]
	v_lshlrev_b32_e32 v120, 16, v53
	v_and_b32_e32 v121, 0xffff0000, v53
	v_lshlrev_b32_e32 v122, 16, v57
	v_and_b32_e32 v123, 0xffff0000, v57
	v_pk_mul_f32 v[128:129], v[120:121], v[122:123]
	v_pk_mul_f32 v[134:135], v[124:125], v[76:77]
	v_pk_fma_f32 v[134:135], v[126:127], v[84:85], v[134:135]
	v_pk_fma_f32 v[134:135], v[128:129], v[92:93], v[134:135]
	v_lshlrev_b32_e32 v120, 16, v61
	v_and_b32_e32 v121, 0xffff0000, v61
	v_pk_mul_f32 v[134:135], v[120:121], v[134:135]
	v_lshlrev_b32_e32 v130, 16, v65
	v_and_b32_e32 v131, 0xffff0000, v65
	v_mul_f32_e32 v132, 0xbfb8aa3b, v130
	v_mul_f32_e32 v133, 0xbfb8aa3b, v131
	v_exp_f32_e32 v132, v132
	v_exp_f32_e32 v133, v133
	s_nop 0
	v_pk_add_f32 v[132:133], v[132:133], 1.0 op_sel_hi:[1,0]
	v_div_scale_f32 v136, s[12:13], v132, v132, v130
	v_rcp_f32_e32 v137, v136
	s_nop 0
	v_fma_f32 v138, -v136, v137, 1.0
	v_fmac_f32_e32 v137, v138, v137
	v_div_scale_f32 v138, vcc, v130, v132, v130
	v_mul_f32_e32 v139, v138, v137
	v_fma_f32 v119, -v136, v139, v138
	v_fmac_f32_e32 v139, v119, v137
	v_fma_f32 v136, -v136, v139, v138
	v_div_fmas_f32 v136, v136, v137, v139
	v_div_fixup_f32 v120, v136, v132, v130
	v_div_scale_f32 v136, s[12:13], v133, v133, v131
	v_rcp_f32_e32 v137, v136
	s_nop 0
	v_fma_f32 v138, -v136, v137, 1.0
	v_fmac_f32_e32 v137, v138, v137
	v_div_scale_f32 v138, vcc, v131, v133, v131
	v_mul_f32_e32 v139, v138, v137
	v_fma_f32 v119, -v136, v139, v138
	v_fmac_f32_e32 v139, v119, v137
	v_fma_f32 v136, -v136, v139, v138
	v_div_fmas_f32 v136, v136, v137, v139
	v_div_fixup_f32 v121, v136, v133, v131
	v_pk_mul_f32 v[134:135], v[134:135], v[120:121]
	v_cvt_pk_bf16_f32 v143, v134, v135
	global_store_dwordx4 v[104:105], v[140:143], off offset:1344
	global_load_dwordx4 v[34:37], v[96:97], off offset:-704
	global_load_dwordx4 v[38:41], v[96:97], off offset:320
	global_load_dwordx4 v[42:45], v[94:95], off offset:-704
	global_load_dwordx4 v[46:49], v[94:95], off offset:320
	global_load_dwordx4 v[50:53], v[98:99], off offset:-704
	global_load_dwordx4 v[54:57], v[98:99], off offset:320
	global_load_dwordx4 v[58:61], v[94:95], off offset:-1728
	global_load_dwordx4 v[62:65], v[94:95], off offset:1344
	v_mov_b32_e32 v104, v94
	v_mov_b32_e32 v105, v95
	v_mov_b32_e32 v107, v100
	v_lshl_add_u64 v[94:95], v[94:95], 0, s[14:15]
	v_lshl_add_u64 v[96:97], v[96:97], 0, s[14:15]
	v_lshl_add_u64 v[98:99], v[98:99], 0, s[14:15]
	v_add_u32_e32 v100, 4, v100
	s_add_i32 s1, s1, 1
	s_cmp_lg_u32 s1, 8
	s_cbranch_scc1 .Lcvb_loop
	s_waitcnt vmcnt(0)
	s_branch .LBB0_774
